# differential attention tile loop: QK^T and P.V LDS fragment reads issued 6-8 deep ahead of their MFMAs instead of read-wait-MFMA chains
# speedup vs baseline: 1.0347x; 1.0347x over previous
; #define LAS __attribute__((address_space(3)))
; __device__ __forceinline__ float max3f(float a, float b, float c) { float r; asm("v_max3_f32 %0, %1, %2, %3" : "=v"(r) : "v"(a), "v"(b), "v"(c)); return r; }
; template <int NS, int DV, class MaskF> ...
;     ...
;     f32x4 s[NS][4];
; #pragma unroll
;     for (int st = 0; st < NS; ++st)
; #pragma unroll
;         for (int kt = 0; kt < 4; ++kt) {
;             const LAS unsigned char* kp = bufK + (kslot[st] * 64 + kt * 16 + fr) * AT_PITCH + g * 16;
;             const bf16x8 a0 = *(const LAS bf16x8*)kp, a1 = *(const LAS bf16x8*)(kp + 64);
;             const float nm = -mrun[st];
;             f32x4 z = {nm, nm, nm, nm};
;             z = MFMA16(a0, qf[st][0], z); z = MFMA16(a1, qf[st][1], z);
;             s[st][kt] = z;
;         }
;     if (masked) {
; #pragma unroll
;         for (int st = 0; st < NS; ++st)
; #pragma unroll
;             for (int kt = 0; kt < 4; ++kt)
; #pragma unroll
;                 for (int i = 0; i < 4; ++i) s[st][kt][i] = mf(s[st][kt][i], st, kt * 16 + g * 4 + i);
;     } else {
;         __builtin_amdgcn_sched_group_barrier(0x100, 4, 0);
; #pragma unroll
;         for (int i = 0; i < NS * 8; ++i) { __builtin_amdgcn_sched_group_barrier(0x008, 1, 0); __builtin_amdgcn_sched_group_barrier(0x100, 1, 0); }
;     }
;     __builtin_amdgcn_sched_barrier(0);
;     float mxs[NS]; bool slow = first;
; #pragma unroll
;     for (int st = 0; st < NS; ++st) {
;         float mx = max3f(s[st][0][0], s[st][0][1], s[st][0][2]);
;         mx = max3f(mx, s[st][0][3], s[st][1][0]); mx = max3f(mx, s[st][1][1], s[st][1][2]); mx = max3f(mx, s[st][1][3], s[st][2][0]);
;         mx = max3f(mx, s[st][2][1], s[st][2][2]); mx = max3f(mx, s[st][2][3], s[st][3][0]); mx = max3f(mx, s[st][3][1], s[st][3][2]); mx = max3f(mx, s[st][3][3], mx);
;         mx = max3f(mx, __shfl_xor(mx, 16), mx); mx = max3f(mx, __shfl_xor(mx, 32), mx);
;         mxs[st] = mx; slow = slow || (mx > 8.0f);
;     }
;     if (__any(slow)) {
; #pragma unroll
;         for (int dt = 0; dt < DV / 16; ++dt)
; #pragma unroll
;             for (int j = 0; j < 2; ++j) {
;                 const bf16x8 va = *(const LAS bf16x8*)(bufV + (128 + vrow0 + dt * 16 + fr) * AT_PITCH + (j * 32 + g * 8) * 2);
; #pragma unroll
;                 for (int st = 0; st < NS; ++st) o[st][dt] = MFMA16(va, pkp[st][j], o[st][dt]);
;             }
.LBB0_650:
	s_mul_i32 s14, s13, 0xa000
	v_add_u32_e32 v190, s14, v227
	ds_read_b128 v[146:149], v190
	ds_read_b128 v[150:153], v190 offset:64
	ds_read_b128 v[154:157], v190 offset:2560
	ds_read_b128 v[158:161], v190 offset:2624
	ds_read_b128 v[182:185], v190 offset:5120
	ds_read_b128 v[186:189], v190 offset:5184
	v_xor_b32_e32 v126, 0x80000000, v173
	v_xor_b32_e32 v138, 0x80000000, v172
	v_mov_b32_e32 v127, v126
	v_mov_b32_e32 v128, v126
	v_mov_b32_e32 v129, v126
	v_mov_b32_e32 v139, v138
	v_mov_b32_e32 v140, v138
	v_mov_b32_e32 v141, v138
	s_mul_i32 s15, s15, 0xa000
	s_add_i32 s15, s15, 0
	s_waitcnt lgkmcnt(5)
	v_mfma_f32_16x16x32_bf16 v[114:117], v[146:149], v[2:5], v[126:129]
	ds_read_b128 v[146:149], v190 offset:7680
	s_waitcnt lgkmcnt(5)
	v_mfma_f32_16x16x32_bf16 v[114:117], v[150:153], v[6:9], v[114:117]
	ds_read_b128 v[150:153], v190 offset:7744
	s_waitcnt lgkmcnt(5)
	v_mfma_f32_16x16x32_bf16 v[118:121], v[154:157], v[2:5], v[126:129]
	ds_read_b128 v[154:157], v190 offset:10240
	s_waitcnt lgkmcnt(5)
	v_mfma_f32_16x16x32_bf16 v[118:121], v[158:161], v[6:9], v[118:121]
	ds_read_b128 v[158:161], v190 offset:10304
	s_waitcnt lgkmcnt(5)
	v_mfma_f32_16x16x32_bf16 v[122:125], v[182:185], v[2:5], v[126:129]
	ds_read_b128 v[182:185], v190 offset:12800
	s_waitcnt lgkmcnt(5)
	v_mfma_f32_16x16x32_bf16 v[122:125], v[186:189], v[6:9], v[122:125]
	ds_read_b128 v[186:189], v190 offset:12864
	s_waitcnt lgkmcnt(5)
	v_mfma_f32_16x16x32_bf16 v[126:129], v[146:149], v[2:5], v[126:129]
	ds_read_b128 v[146:149], v190 offset:15360
	s_waitcnt lgkmcnt(5)
	v_mfma_f32_16x16x32_bf16 v[126:129], v[150:153], v[6:9], v[126:129]
	ds_read_b128 v[150:153], v190 offset:15424
	s_waitcnt lgkmcnt(5)
	v_mfma_f32_16x16x32_bf16 v[134:137], v[154:157], v[10:13], v[138:141]
	ds_read_b128 v[154:157], v190 offset:17920
	s_waitcnt lgkmcnt(5)
	v_mfma_f32_16x16x32_bf16 v[134:137], v[158:161], v[14:17], v[134:137]
	ds_read_b128 v[158:161], v190 offset:17984
	s_waitcnt lgkmcnt(5)
	v_mfma_f32_16x16x32_bf16 v[142:145], v[182:185], v[10:13], v[138:141]
	s_waitcnt lgkmcnt(4)
	v_mfma_f32_16x16x32_bf16 v[142:145], v[186:189], v[14:17], v[142:145]
	s_waitcnt lgkmcnt(3)
	v_mfma_f32_16x16x32_bf16 v[130:133], v[146:149], v[10:13], v[138:141]
	s_waitcnt lgkmcnt(2)
	v_mfma_f32_16x16x32_bf16 v[130:133], v[150:153], v[14:17], v[130:133]
	s_waitcnt lgkmcnt(1)
	v_mfma_f32_16x16x32_bf16 v[138:141], v[154:157], v[10:13], v[138:141]
	s_waitcnt lgkmcnt(0)
	v_mfma_f32_16x16x32_bf16 v[138:141], v[158:161], v[14:17], v[138:141]
	v_max3_f32 v146, v114, v115, v116
	v_max3_f32 v148, v134, v135, v136
	s_mov_b32 s16, 0x41000000
	v_max3_f32 v146, v146, v117, v118
	v_max3_f32 v148, v148, v137, v142
	v_add3_u32 v179, s15, v226, v0
	v_max3_f32 v146, v146, v119, v120
	v_max3_f32 v148, v148, v143, v144
	v_add3_u32 v180, s15, v225, v0
	v_max3_f32 v146, v146, v121, v122
	v_max3_f32 v148, v148, v145, v130
	v_add3_u32 v178, s15, v224, v0
	v_max3_f32 v146, v146, v123, v124
	v_max3_f32 v148, v148, v131, v132
	s_nop 0
	v_max3_f32 v146, v146, v125, v126
	v_max3_f32 v148, v148, v133, v138
	s_nop 0
	v_max3_f32 v146, v146, v127, v128
	v_max3_f32 v148, v148, v139, v140
	s_nop 0
	v_max3_f32 v146, v146, v129, v146
	ds_bpermute_b32 v147, v194, v146
	v_max3_f32 v148, v148, v141, v148
	ds_bpermute_b32 v149, v194, v148
	s_waitcnt lgkmcnt(1)
	v_max3_f32 v146, v146, v147, v146
	ds_bpermute_b32 v147, v196, v146
	s_waitcnt lgkmcnt(1)
	v_max3_f32 v148, v148, v149, v148
	ds_bpermute_b32 v149, v196, v148
	s_waitcnt lgkmcnt(1)
	v_max3_f32 v147, v146, v147, v146
	s_waitcnt lgkmcnt(0)
	v_max3_f32 v146, v148, v149, v148
	s_nop 0
	v_max_f32_e32 v148, v146, v146
	v_max_f32_e32 v149, v147, v147
	v_max_f32_e32 v150, v149, v148
	v_cmp_lt_f32_e32 vcc, s16, v150
	s_cbranch_vccz .LBB0_652
	ds_read_b128 v[150:153], v179 offset:20480
	s_mov_b32 s15, 0xe0ad78ec
	v_cmp_ngt_f32_e32 vcc, s15, v147
	s_waitcnt lgkmcnt(0)
	v_mfma_f32_16x16x32_bf16 v[38:41], v[150:153], v[54:57], v[38:41]
	v_mfma_f32_16x16x32_bf16 v[78:81], v[150:153], v[98:101], v[78:81]
	ds_read_b128 v[150:153], v179 offset:20544
	s_waitcnt lgkmcnt(0)
	v_mfma_f32_16x16x32_bf16 v[38:41], v[150:153], v[46:49], v[38:41]
	v_mfma_f32_16x16x32_bf16 v[78:81], v[150:153], v[70:73], v[78:81]
	ds_read_b128 v[150:153], v179 offset:23040
	s_waitcnt lgkmcnt(0)
	v_mfma_f32_16x16x32_bf16 v[34:37], v[150:153], v[54:57], v[34:37]
	v_mfma_f32_16x16x32_bf16 v[74:77], v[150:153], v[98:101], v[74:77]
	ds_read_b128 v[150:153], v179 offset:23104
	s_waitcnt lgkmcnt(0)
	v_mfma_f32_16x16x32_bf16 v[34:37], v[150:153], v[46:49], v[34:37]
	v_mfma_f32_16x16x32_bf16 v[74:77], v[150:153], v[70:73], v[74:77]
	ds_read_b128 v[150:153], v179 offset:25600
	s_waitcnt lgkmcnt(0)
	v_mfma_f32_16x16x32_bf16 v[42:45], v[150:153], v[54:57], v[42:45]
	v_mfma_f32_16x16x32_bf16 v[82:85], v[150:153], v[98:101], v[82:85]
	ds_read_b128 v[150:153], v179 offset:25664
	s_waitcnt lgkmcnt(0)
	v_mfma_f32_16x16x32_bf16 v[42:45], v[150:153], v[46:49], v[42:45]
	v_mfma_f32_16x16x32_bf16 v[82:85], v[150:153], v[70:73], v[82:85]
	ds_read_b128 v[150:153], v180 offset:20480
	s_waitcnt lgkmcnt(0)
	v_mfma_f32_16x16x32_bf16 v[50:53], v[150:153], v[54:57], v[50:53]
	v_mfma_f32_16x16x32_bf16 v[86:89], v[150:153], v[98:101], v[86:89]
	ds_read_b128 v[150:153], v180 offset:20544
	s_waitcnt lgkmcnt(0)
	v_mfma_f32_16x16x32_bf16 v[50:53], v[150:153], v[46:49], v[50:53]
	v_mfma_f32_16x16x32_bf16 v[86:89], v[150:153], v[70:73], v[86:89]
	ds_read_b128 v[150:153], v179 offset:30720
	s_waitcnt lgkmcnt(0)
	v_mfma_f32_16x16x32_bf16 v[62:65], v[150:153], v[54:57], v[62:65]
	v_mfma_f32_16x16x32_bf16 v[94:97], v[150:153], v[98:101], v[94:97]
	ds_read_b128 v[150:153], v179 offset:30784
	s_waitcnt lgkmcnt(0)
; #define LAS __attribute__((address_space(3)))
; __device__ __forceinline__ float ex2(float x) { return __builtin_amdgcn_exp2f(x); }
; #define MFMA16(a, b, c) __builtin_amdgcn_mfma_f32_16x16x32_bf16((a), (b), (c), 0, 0, 0)
; template <int NS, int DV, class MaskF> ...
;     ...
;     if (__any(slow)) {
; #pragma unroll
;         for (int dt = 0; dt < DV / 16; ++dt)
; #pragma unroll
;             for (int j = 0; j < 2; ++j) {
;                 const bf16x8 va = *(const LAS bf16x8*)(bufV + (128 + vrow0 + dt * 16 + fr) * AT_PITCH + (j * 32 + g * 8) * 2);
; #pragma unroll
;                 for (int st = 0; st < NS; ++st) o[st][dt] = MFMA16(va, pkp[st][j], o[st][dt]);
;             }
; #pragma unroll
;         for (int st = 0; st < NS; ++st) {
;             const float d = mxs[st] < -1e20f ? 0.f : (first ? mxs[st] : fmaxf(mxs[st], 0.f));
;             mrun[st] += d; const float alpha = ex2(-d);
;             lrun[st] *= alpha;
; #pragma unroll
;             for (int kt = 0; kt < 4; ++kt) s[st][kt] = s[st][kt] - d;
; #pragma unroll
;             for (int dt = 0; dt < DV / 16; ++dt) o[st][dt] = o[st][dt] * alpha;
;             pkp[st][0] = (bf16x8){0, 0, 0, 0, 0, 0, 0, 0}; pkp[st][1] = pkp[st][0];
;         }
	v_mfma_f32_16x16x32_bf16 v[62:65], v[150:153], v[46:49], v[62:65]
	v_mfma_f32_16x16x32_bf16 v[94:97], v[150:153], v[70:73], v[94:97]
	ds_read_b128 v[150:153], v179 offset:33280
	s_waitcnt lgkmcnt(0)
	v_mfma_f32_16x16x32_bf16 v[58:61], v[150:153], v[54:57], v[58:61]
	v_mfma_f32_16x16x32_bf16 v[90:93], v[150:153], v[98:101], v[90:93]
	ds_read_b128 v[150:153], v179 offset:33344
	s_waitcnt lgkmcnt(0)
	v_mfma_f32_16x16x32_bf16 v[58:61], v[150:153], v[46:49], v[58:61]
	v_mfma_f32_16x16x32_bf16 v[90:93], v[150:153], v[70:73], v[90:93]
	ds_read_b128 v[150:153], v179 offset:35840
	s_waitcnt lgkmcnt(0)
	v_mfma_f32_16x16x32_bf16 v[66:69], v[150:153], v[54:57], v[66:69]
	v_mfma_f32_16x16x32_bf16 v[102:105], v[150:153], v[98:101], v[102:105]
	ds_read_b128 v[150:153], v179 offset:35904
	s_waitcnt lgkmcnt(0)
	v_mfma_f32_16x16x32_bf16 v[66:69], v[150:153], v[46:49], v[66:69]
	v_mfma_f32_16x16x32_bf16 v[102:105], v[150:153], v[70:73], v[102:105]
	ds_read_b128 v[150:153], v178 offset:20480
	s_waitcnt lgkmcnt(0)
	v_mfma_f32_16x16x32_bf16 v[54:57], v[150:153], v[54:57], v[106:109]
	s_nop 2
	ds_read_b128 v[106:109], v178 offset:20544
	v_mfma_f32_16x16x32_bf16 v[98:101], v[150:153], v[98:101], v[110:113]
	s_waitcnt lgkmcnt(0)
	v_mfma_f32_16x16x32_bf16 v[54:57], v[106:109], v[46:49], v[54:57]
	v_mfma_f32_16x16x32_bf16 v[46:49], v[106:109], v[70:73], v[98:101]
	v_max_f32_e32 v70, 0, v149
	v_max_f32_e32 v72, 0, v148
	v_cndmask_b32_e32 v71, 0, v70, vcc
	v_cmp_ngt_f32_e32 vcc, s15, v146
	v_sub_f32_e32 v114, v114, v71
	v_sub_f32_e32 v115, v115, v71
	v_cndmask_b32_e32 v70, 0, v72, vcc
	v_exp_f32_e64 v72, -v71
	v_pk_add_f32 v[172:173], v[172:173], v[70:71]
	v_sub_f32_e32 v134, v134, v70
	v_sub_f32_e32 v135, v135, v70
	v_pk_mul_f32 v[106:107], v[72:73], v[54:55] op_sel_hi:[0,1]
	v_exp_f32_e64 v54, -v70
	v_mov_b32_e32 v55, v72
	v_sub_f32_e32 v136, v136, v70
	v_sub_f32_e32 v137, v137, v70
	v_sub_f32_e32 v142, v142, v70
	v_sub_f32_e32 v143, v143, v70
	v_sub_f32_e32 v144, v144, v70
	v_sub_f32_e32 v145, v145, v70
	v_sub_f32_e32 v130, v130, v70
	v_sub_f32_e32 v131, v131, v70
	v_sub_f32_e32 v132, v132, v70
	v_sub_f32_e32 v133, v133, v70
	v_sub_f32_e32 v138, v138, v70
	v_sub_f32_e32 v139, v139, v70
	v_sub_f32_e32 v140, v140, v70
	v_sub_f32_e32 v141, v141, v70
	v_mov_b32_e32 v70, 0
	v_sub_f32_e32 v116, v116, v71
	v_sub_f32_e32 v117, v117, v71
	v_sub_f32_e32 v118, v118, v71
	v_sub_f32_e32 v119, v119, v71
	v_sub_f32_e32 v120, v120, v71
	v_sub_f32_e32 v121, v121, v71
	v_sub_f32_e32 v122, v122, v71
	v_sub_f32_e32 v123, v123, v71
	v_sub_f32_e32 v124, v124, v71
	v_sub_f32_e32 v125, v125, v71
	v_sub_f32_e32 v126, v126, v71
	v_sub_f32_e32 v127, v127, v71
	v_sub_f32_e32 v128, v128, v71
	v_sub_f32_e32 v129, v129, v71
	v_pk_mul_f32 v[40:41], v[72:73], v[40:41] op_sel_hi:[0,1]
	v_pk_mul_f32 v[38:39], v[72:73], v[38:39] op_sel_hi:[0,1]
	v_pk_mul_f32 v[36:37], v[72:73], v[36:37] op_sel_hi:[0,1]
	v_pk_mul_f32 v[34:35], v[72:73], v[34:35] op_sel_hi:[0,1]
	v_pk_mul_f32 v[44:45], v[72:73], v[44:45] op_sel_hi:[0,1]
	v_pk_mul_f32 v[42:43], v[72:73], v[42:43] op_sel_hi:[0,1]
	v_pk_mul_f32 v[52:53], v[72:73], v[52:53] op_sel_hi:[0,1]
	v_pk_mul_f32 v[50:51], v[72:73], v[50:51] op_sel_hi:[0,1]
	v_pk_mul_f32 v[64:65], v[72:73], v[64:65] op_sel_hi:[0,1]
	v_pk_mul_f32 v[62:63], v[72:73], v[62:63] op_sel_hi:[0,1]
	v_pk_mul_f32 v[60:61], v[72:73], v[60:61] op_sel_hi:[0,1]
	v_pk_mul_f32 v[58:59], v[72:73], v[58:59] op_sel_hi:[0,1]
	v_pk_mul_f32 v[68:69], v[72:73], v[68:69] op_sel_hi:[0,1]
	v_pk_mul_f32 v[66:67], v[72:73], v[66:67] op_sel_hi:[0,1]
	v_pk_mul_f32 v[108:109], v[72:73], v[56:57] op_sel_hi:[0,1]
	v_pk_mul_f32 v[174:175], v[174:175], v[54:55]
	v_pk_mul_f32 v[80:81], v[54:55], v[80:81] op_sel_hi:[0,1]
	v_pk_mul_f32 v[78:79], v[54:55], v[78:79] op_sel_hi:[0,1]
	v_pk_mul_f32 v[76:77], v[54:55], v[76:77] op_sel_hi:[0,1]
	v_pk_mul_f32 v[74:75], v[54:55], v[74:75] op_sel_hi:[0,1]
	v_pk_mul_f32 v[84:85], v[54:55], v[84:85] op_sel_hi:[0,1]
	v_pk_mul_f32 v[82:83], v[54:55], v[82:83] op_sel_hi:[0,1]
	v_pk_mul_f32 v[88:89], v[54:55], v[88:89] op_sel_hi:[0,1]
	v_pk_mul_f32 v[86:87], v[54:55], v[86:87] op_sel_hi:[0,1]
	v_pk_mul_f32 v[96:97], v[54:55], v[96:97] op_sel_hi:[0,1]
	v_pk_mul_f32 v[94:95], v[54:55], v[94:95] op_sel_hi:[0,1]
	v_pk_mul_f32 v[92:93], v[54:55], v[92:93] op_sel_hi:[0,1]
	v_pk_mul_f32 v[90:91], v[54:55], v[90:91] op_sel_hi:[0,1]
	v_pk_mul_f32 v[104:105], v[54:55], v[104:105] op_sel_hi:[0,1]
	v_pk_mul_f32 v[102:103], v[54:55], v[102:103] op_sel_hi:[0,1]
	v_pk_mul_f32 v[112:113], v[54:55], v[48:49] op_sel_hi:[0,1]
	v_pk_mul_f32 v[110:111], v[54:55], v[46:47] op_sel_hi:[0,1]
	v_mov_b32_e32 v71, v70
	v_mov_b32_e32 v72, v70
	v_mov_b32_e32 v73, v70
	v_mov_b32_e32 v98, v70
	v_mov_b32_e32 v99, v70
	v_mov_b32_e32 v100, v70
	v_mov_b32_e32 v101, v70
	v_mov_b32_e32 v46, v70
	v_mov_b32_e32 v47, v70
	v_mov_b32_e32 v48, v70
	v_mov_b32_e32 v49, v70
	v_mov_b32_e32 v54, v70
	v_mov_b32_e32 v55, v70
	v_mov_b32_e32 v56, v70
	v_mov_b32_e32 v57, v70
; #define LAS __attribute__((address_space(3)))
; __device__ __forceinline__ unsigned pk2(float lo, float hi) { unsigned r; asm volatile("v_cvt_pk_bf16_f32 %0, %1, %2" : "=v"(r) : "v"(lo), "v"(hi)); return r; }
; __device__ __forceinline__ float ex2(float x) { return __builtin_amdgcn_exp2f(x); }
; #define MFMA16(a, b, c) __builtin_amdgcn_mfma_f32_16x16x32_bf16((a), (b), (c), 0, 0, 0)
; template <int NS, int DV, class MaskF> ...
;     ...
;     {
;         bf16x8 pkn[NS][2];
; #pragma unroll
;         for (int st = 0; st < NS; ++st) {
;             float ps = 0.f;
; #pragma unroll
;             for (int kt = 0; kt < 4; ++kt)
; #pragma unroll
;                 for (int i = 0; i < 4; ++i) { const float p = ex2(s[st][kt][i]); ps += p; s[st][kt][i] = p; }
;             lrun[st] += ps;
; #pragma unroll
;             for (int j = 0; j < 2; ++j) {
;                 u32x4 w; w.x = pk2(s[st][2 * j][0], s[st][2 * j][1]); w.y = pk2(s[st][2 * j][2], s[st][2 * j][3]);
;                 w.z = pk2(s[st][2 * j + 1][0], s[st][2 * j + 1][1]); w.w = pk2(s[st][2 * j + 1][2], s[st][2 * j + 1][3]);
;                 pkn[st][j] = __builtin_bit_cast(bf16x8, w);
;             }
;         }
; #pragma unroll
;         for (int dt = 0; dt < DV / 16; ++dt)
; #pragma unroll
;             for (int j = 0; j < 2; ++j) {
;                 const bf16x8 va = *(const LAS bf16x8*)(bufV + (128 + vrow0 + dt * 16 + fr) * AT_PITCH + (j * 32 + g * 8) * 2);
; #pragma unroll
;                 for (int st = 0; st < NS; ++st) o[st][dt] = MFMA16(va, pkp[st][j], o[st][dt]);
;             }
; #pragma unroll
;         for (int st = 0; st < NS; ++st) { pkp[st][0] = pkn[st][0]; pkp[st][1] = pkn[st][1]; }
.LBB0_652:
	v_mov_b32_e32 v154, v54
	v_mov_b32_e32 v155, v55
	v_mov_b32_e32 v156, v56
	v_mov_b32_e32 v157, v57
	v_mov_b32_e32 v146, v46
	v_mov_b32_e32 v147, v47
	v_mov_b32_e32 v148, v48
	v_mov_b32_e32 v149, v49
	v_mov_b32_e32 v158, v98
	v_mov_b32_e32 v159, v99
	v_mov_b32_e32 v160, v100
	v_mov_b32_e32 v161, v101
	v_mov_b32_e32 v150, v70
	v_mov_b32_e32 v151, v71
	v_mov_b32_e32 v152, v72
	v_mov_b32_e32 v153, v73
	v_exp_f32_e32 v71, v114
	v_exp_f32_e32 v70, v134
	v_exp_f32_e32 v73, v115
	v_exp_f32_e32 v72, v135
	v_exp_f32_e32 v101, v116
	v_exp_f32_e32 v100, v136
	v_exp_f32_e32 v115, v117
	v_exp_f32_e32 v114, v137
	v_exp_f32_e32 v117, v118
	v_exp_f32_e32 v116, v142
	v_pk_add_f32 v[98:99], v[70:71], 0 op_sel_hi:[1,0]
	v_exp_f32_e32 v119, v119
	v_exp_f32_e32 v118, v143
	v_pk_add_f32 v[98:99], v[72:73], v[98:99]
	v_exp_f32_e32 v183, v120
	v_exp_f32_e32 v182, v144
	v_pk_add_f32 v[98:99], v[100:101], v[98:99]
	v_exp_f32_e32 v121, v121
	v_exp_f32_e32 v120, v145
	v_pk_add_f32 v[98:99], v[114:115], v[98:99]
	v_exp_f32_e32 v185, v122
	v_pk_add_f32 v[98:99], v[116:117], v[98:99]
	v_exp_f32_e32 v184, v130
	v_exp_f32_e32 v123, v123
	v_pk_add_f32 v[98:99], v[118:119], v[98:99]
	v_exp_f32_e32 v122, v131
	v_exp_f32_e32 v187, v124
	v_pk_add_f32 v[98:99], v[182:183], v[98:99]
	v_exp_f32_e32 v186, v132
	v_exp_f32_e32 v125, v125
	v_pk_add_f32 v[98:99], v[120:121], v[98:99]
	v_exp_f32_e32 v124, v133
	v_exp_f32_e32 v189, v126
	v_exp_f32_e32 v188, v138
	v_pk_add_f32 v[98:99], v[184:185], v[98:99]
	v_exp_f32_e32 v127, v127
	v_exp_f32_e32 v126, v139
	v_pk_add_f32 v[98:99], v[122:123], v[98:99]
	v_exp_f32_e32 v191, v128
	v_exp_f32_e32 v190, v140
	v_pk_add_f32 v[98:99], v[186:187], v[98:99]
	v_exp_f32_e32 v129, v129
	v_exp_f32_e32 v128, v141
	ds_read_b128 v[130:133], v179 offset:20480
	ds_read_b128 v[134:137], v179 offset:20544
	ds_read_b128 v[138:141], v179 offset:23040
	ds_read_b128 v[142:145], v179 offset:23104
	v_pk_add_f32 v[98:99], v[124:125], v[98:99]
	v_cvt_pk_bf16_f32 v54, v71, v73
	v_cvt_pk_bf16_f32 v55, v101, v115
	v_cvt_pk_bf16_f32 v56, v117, v119
	v_cvt_pk_bf16_f32 v57, v183, v121
	v_cvt_pk_bf16_f32 v46, v185, v123
	s_nop 0
	v_pk_add_f32 v[98:99], v[188:189], v[98:99]
	v_cvt_pk_bf16_f32 v47, v187, v125
	v_cvt_pk_bf16_f32 v48, v189, v127
	v_cvt_pk_bf16_f32 v49, v191, v129
	s_nop 0
	v_pk_add_f32 v[98:99], v[126:127], v[98:99]
	s_nop 0
	v_pk_add_f32 v[98:99], v[190:191], v[98:99]
	s_nop 0
	v_pk_add_f32 v[98:99], v[128:129], v[98:99]
	s_nop 0
	v_pk_add_f32 v[174:175], v[98:99], v[174:175]
	v_cvt_pk_bf16_f32 v98, v70, v72
	v_cvt_pk_bf16_f32 v99, v100, v114
	v_cvt_pk_bf16_f32 v100, v116, v118
	v_cvt_pk_bf16_f32 v101, v182, v120
	v_cvt_pk_bf16_f32 v70, v184, v122
	v_cvt_pk_bf16_f32 v71, v186, v124
	v_cvt_pk_bf16_f32 v72, v188, v126
	v_cvt_pk_bf16_f32 v73, v190, v128
	ds_read_b128 v[114:117], v179 offset:25600
	ds_read_b128 v[118:121], v179 offset:25664
	ds_read_b128 v[122:125], v180 offset:20480
	ds_read_b128 v[126:129], v180 offset:20544
	s_waitcnt lgkmcnt(7)
	v_mfma_f32_16x16x32_bf16 v[38:41], v[130:133], v[154:157], v[38:41]
	v_mfma_f32_16x16x32_bf16 v[78:81], v[130:133], v[158:161], v[78:81]
	ds_read_b128 v[130:133], v179 offset:30720
	s_waitcnt lgkmcnt(7)
	v_mfma_f32_16x16x32_bf16 v[38:41], v[134:137], v[146:149], v[38:41]
	v_mfma_f32_16x16x32_bf16 v[78:81], v[134:137], v[150:153], v[78:81]
	ds_read_b128 v[134:137], v179 offset:30784
	s_waitcnt lgkmcnt(7)
	v_mfma_f32_16x16x32_bf16 v[34:37], v[138:141], v[154:157], v[34:37]
	v_mfma_f32_16x16x32_bf16 v[74:77], v[138:141], v[158:161], v[74:77]
	ds_read_b128 v[138:141], v179 offset:33280
	s_waitcnt lgkmcnt(7)
	v_mfma_f32_16x16x32_bf16 v[34:37], v[142:145], v[146:149], v[34:37]
	v_mfma_f32_16x16x32_bf16 v[74:77], v[142:145], v[150:153], v[74:77]
	ds_read_b128 v[142:145], v179 offset:33344
	s_waitcnt lgkmcnt(7)
	v_mfma_f32_16x16x32_bf16 v[42:45], v[114:117], v[154:157], v[42:45]
	v_mfma_f32_16x16x32_bf16 v[82:85], v[114:117], v[158:161], v[82:85]
	ds_read_b128 v[114:117], v179 offset:35840
	s_waitcnt lgkmcnt(7)
	v_mfma_f32_16x16x32_bf16 v[42:45], v[118:121], v[146:149], v[42:45]
	v_mfma_f32_16x16x32_bf16 v[82:85], v[118:121], v[150:153], v[82:85]
	ds_read_b128 v[118:121], v179 offset:35904
	s_waitcnt lgkmcnt(7)
	v_mfma_f32_16x16x32_bf16 v[50:53], v[122:125], v[154:157], v[50:53]
	v_mfma_f32_16x16x32_bf16 v[86:89], v[122:125], v[158:161], v[86:89]
	ds_read_b128 v[122:125], v178 offset:20480
	s_waitcnt lgkmcnt(7)
	v_mfma_f32_16x16x32_bf16 v[50:53], v[126:129], v[146:149], v[50:53]
	v_mfma_f32_16x16x32_bf16 v[86:89], v[126:129], v[150:153], v[86:89]
	ds_read_b128 v[126:129], v178 offset:20544
	s_waitcnt lgkmcnt(7)
	v_mfma_f32_16x16x32_bf16 v[62:65], v[130:133], v[154:157], v[62:65]
	v_mfma_f32_16x16x32_bf16 v[94:97], v[130:133], v[158:161], v[94:97]
	s_waitcnt lgkmcnt(6)
	v_mfma_f32_16x16x32_bf16 v[62:65], v[134:137], v[146:149], v[62:65]
	v_mfma_f32_16x16x32_bf16 v[94:97], v[134:137], v[150:153], v[94:97]
	s_waitcnt lgkmcnt(5)
	v_mfma_f32_16x16x32_bf16 v[58:61], v[138:141], v[154:157], v[58:61]
	v_mfma_f32_16x16x32_bf16 v[90:93], v[138:141], v[158:161], v[90:93]
	s_waitcnt lgkmcnt(4)
	v_mfma_f32_16x16x32_bf16 v[58:61], v[142:145], v[146:149], v[58:61]
	v_mfma_f32_16x16x32_bf16 v[90:93], v[142:145], v[150:153], v[90:93]
	s_waitcnt lgkmcnt(3)
	v_mfma_f32_16x16x32_bf16 v[66:69], v[114:117], v[154:157], v[66:69]
	v_mfma_f32_16x16x32_bf16 v[102:105], v[114:117], v[158:161], v[102:105]
	s_waitcnt lgkmcnt(2)
	v_mfma_f32_16x16x32_bf16 v[66:69], v[118:121], v[146:149], v[66:69]
	v_mfma_f32_16x16x32_bf16 v[102:105], v[118:121], v[150:153], v[102:105]
	s_waitcnt lgkmcnt(1)
	v_mfma_f32_16x16x32_bf16 v[106:109], v[122:125], v[154:157], v[106:109]
	v_mfma_f32_16x16x32_bf16 v[110:113], v[122:125], v[158:161], v[110:113]
	s_waitcnt lgkmcnt(0)
	v_mfma_f32_16x16x32_bf16 v[106:109], v[126:129], v[146:149], v[106:109]
	v_mfma_f32_16x16x32_bf16 v[110:113], v[126:129], v[150:153], v[110:113]
	s_add_i32 s0, s0, 64
	s_add_i32 s12, s12, 1
	s_mov_b64 s[16:17], 0x80
	s_cmpk_lg_i32 s0, 0x20c0
	v_lshl_add_u64 v[176:177], v[176:177], 0, s[16:17]
	s_barrier
	s_cbranch_scc0 .LBB0_641
	s_mov_b32 s15, s13
	s_branch .LBB0_646
